# plus A2 loop: next-tile global loads at iteration top, LDS stores at start of softmax 1 (drain under compute instead of before the barrier)
# baseline (speedup 1.0000x reference)
; #define SLOAD2(k0) do { vs0 = *reinterpret_cast<const bf16x8*>(&Vh[(long)((k0) + sr) * ldv + sc]); vs1 = *reinterpret_cast<const bf16x8*>(&Vh[(long)((k0) + 32 + sr) * ldv + sc]); \
;     ks0 = *reinterpret_cast<const bf16x8*>(&Kh[(long)((k0) + sr) * ldk + sc]); ks1 = *reinterpret_cast<const bf16x8*>(&Kh[(long)((k0) + 32 + sr) * ldk + sc]); } while (0)
; __device__ __forceinline__ void attn_unit_A2(const bf16_t* __restrict__ Qb, int ldq, const bf16_t* __restrict__ Kh, int ldk, const bf16_t* __restrict__ Vh, int ldv, int nkeys, int q0, ...
;     ...
;     if (j + 1 < NT) SLOAD2(kt0 + KVBLK);
.LBB0_335:
	s_cmpk_eq_u32 s63, 0xff00
	s_cbranch_scc1 .Lmy_A_noload
	v_add_co_u32_e32 v176, vcc, 0xfffb0000, v198
	s_nop 1
	v_addc_co_u32_e32 v177, vcc, -1, v199, vcc
	global_load_dwordx4 v[184:187], v[176:177], off offset:-1024
	global_load_dwordx4 v[176:179], v[176:177], off
	global_load_dwordx4 v[180:183], v[198:199], off
	global_load_dwordx4 v[188:191], v[198:199], off offset:-1024

; #define SWRITE2(b) do { *(bf16x8*)(V_lds + (b) * SHM_V + vst0) = vs0; *(bf16x8*)(V_lds + (b) * SHM_V + vst1) = vs1; \
;     *(bf16x8*)(K_lds + (b) * SHM_K + KSWZ(sr, sc * 2)) = ks0; *(bf16x8*)(K_lds + (b) * SHM_K + KSWZ(32 + sr, sc * 2)) = ks1; } while (0)
; __device__ __forceinline__ void attn_unit_A2(const bf16_t* __restrict__ Qb, int ldq, const bf16_t* __restrict__ Kh, int ldk, const bf16_t* __restrict__ Vh, int ldv, int nkeys, int q0, ...
;     ...
;     if (j + 1 < NT) { asm volatile("s_waitcnt vmcnt(0)" ::: "memory"); SWRITE2(b ^ 1); }
.LBB0_343:
	s_cmpk_eq_u32 s63, 0xff00
	s_cbranch_scc1 .Lmy_A_nowrite
	s_xor_b32 vcc_lo, s64, 0x4000
	v_add_u32_e32 v241, vcc_lo, v209
	s_waitcnt vmcnt(0)
	ds_write_b128 v241, v[176:179]
	v_add_u32_e32 v241, vcc_lo, v210
	ds_write_b128 v241, v[180:183]
	v_add_u32_e32 v241, vcc_lo, v212
	ds_write_b128 v241, v[184:187] offset:32768
	v_add_u32_e32 v241, vcc_lo, v213
	ds_write_b128 v241, v[188:191] offset:32768
	s_branch .Lmy_A_sm1

; __device__ __forceinline__ void softmax_tile(f32x16& p0, f32x16& p1, float& m, float& l, float& alpha, float cb, bf16x8& pa0, bf16x8& pa1, bf16x8& pa2, bf16x8& pa3) {
;   float mx_[4] = {p0[0], p0[1], p0[2], p0[3]};
; #pragma unroll
;   for (int r = 4; r < 16; ++r) mx_[r & 3] = fmaxf(mx_[r & 3], p0[r]);
; #pragma unroll
;   for (int r = 0; r < 16; ++r) mx_[r & 3] = fmaxf(mx_[r & 3], p1[r]);
;   float pmax = fmaxf(fmaxf(mx_[0], mx_[1]), fmaxf(mx_[2], mx_[3]));
;   { auto rr = __builtin_amdgcn_permlane32_swap(__float_as_uint(pmax), __float_as_uint(pmax), false, false);
;     pmax = fmaxf(__uint_as_float(rr[0]), __uint_as_float(rr[1])); }
;   pmax += cb;
;   float mn;
;   if (__builtin_expect(__all(pmax - m <= THR2), 1)) { mn = m; alpha = 1.f; }
;   else { mn = fmaxf(m, pmax); alpha = __builtin_amdgcn_exp2f(m - mn); m = mn; }
;   const float off = cb - mn;
; #pragma unroll
;   for (int r = 0; r < 16; ++r) p0[r] = __builtin_amdgcn_exp2f(p0[r] + off);
; #pragma unroll
;   for (int r = 0; r < 16; ++r) p1[r] = __builtin_amdgcn_exp2f(p1[r] + off);
;   float sm_[4] = {p0[0], p0[1], p0[2], p0[3]};
; #pragma unroll
;   for (int r = 4; r < 16; ++r) sm_[r & 3] += p0[r];
; #pragma unroll
;   for (int r = 0; r < 16; ++r) sm_[r & 3] += p1[r];
;   float ps = (sm_[0] + sm_[1]) + (sm_[2] + sm_[3]);
;   { auto rr = __builtin_amdgcn_permlane32_swap(__float_as_uint(ps), __float_as_uint(ps), false, false);
;     ps = __uint_as_float(rr[0]) + __uint_as_float(rr[1]); }
;   l = l * alpha + ps;
;     ...
;   PK4(p0, 0, pa0); PK4(p0, 8, pa1); PK4(p1, 0, pa2); PK4(p1, 8, pa3);
;     ...
; }
.Lmy_A_sm1:
	v_max_f32_e32 v2, v160, v164
	v_max_f32_e32 v3, v161, v165
	v_max_f32_e32 v4, v163, v167
	v_max3_f32 v5, v162, v166, v170
	v_max3_f32 v4, v4, v171, v175
	v_max3_f32 v2, v2, v168, v172
	v_max3_f32 v3, v3, v169, v173
	v_max3_f32 v5, v5, v174, v146
	v_max3_f32 v4, v4, v147, v151
	v_max3_f32 v2, v2, v144, v148
	v_max3_f32 v3, v3, v145, v149
	v_max3_f32 v5, v5, v150, v154
	v_max3_f32 v4, v4, v155, v159
	v_max3_f32 v2, v2, v152, v156
	v_max3_f32 v3, v3, v153, v157
	v_max3_f32 v4, v5, v158, v4
	v_max3_f32 v2, v2, v3, v4
	v_mov_b32_e32 v3, v2
	s_nop 1
	v_permlane32_swap_b32_e32 v2, v3
	v_max_f32_e32 v2, v2, v3
	v_add_f32_e32 v2, v227, v2
	v_sub_f32_e32 v3, v2, v218
	v_cmp_ge_f32_e32 vcc, s48, v3
	s_cmp_eq_u64 vcc, exec
	v_max_f32_e32 v2, v218, v2
	s_cselect_b64 vcc, -1, 0
	v_sub_f32_e32 v3, v218, v2
	v_cndmask_b32_e32 v218, v2, v218, vcc
	v_sub_f32_e32 v2, v227, v218
	v_add_f32_e32 v148, v148, v2
	v_add_f32_e32 v8, v165, v2
	v_exp_f32_e32 v165, v148
	v_add_f32_e32 v148, v149, v2
	v_exp_f32_e32 v3, v3
	v_add_f32_e32 v9, v166, v2
	v_exp_f32_e32 v166, v148
	v_add_f32_e32 v148, v150, v2
	v_exp_f32_e32 v150, v148
	v_add_f32_e32 v148, v151, v2
	v_exp_f32_e32 v151, v148
	v_add_f32_e32 v148, v152, v2
	v_exp_f32_e32 v152, v148
	v_add_f32_e32 v148, v153, v2
	v_cndmask_b32_e64 v223, v3, 1.0, vcc
	v_add_f32_e32 v3, v160, v2
	v_add_f32_e32 v4, v161, v2
	v_add_f32_e32 v5, v162, v2
	v_add_f32_e32 v6, v163, v2
	v_add_f32_e32 v7, v164, v2
	v_add_f32_e32 v10, v167, v2
	v_exp_f32_e32 v153, v148
	v_add_f32_e32 v148, v154, v2
	v_exp_f32_e32 v3, v3
	v_exp_f32_e32 v4, v4
	v_exp_f32_e32 v5, v5
	v_exp_f32_e32 v6, v6
	v_exp_f32_e32 v7, v7
	v_exp_f32_e32 v8, v8
	v_exp_f32_e32 v9, v9
	v_exp_f32_e32 v10, v10
	v_add_f32_e32 v11, v168, v2
	v_add_f32_e32 v12, v169, v2
	v_add_f32_e32 v13, v170, v2
	v_add_f32_e32 v160, v171, v2
	v_exp_f32_e32 v154, v148
	v_add_f32_e32 v148, v155, v2
	v_exp_f32_e32 v11, v11
	v_exp_f32_e32 v12, v12
	v_exp_f32_e32 v13, v13
	v_exp_f32_e32 v160, v160
	v_add_f32_e32 v161, v172, v2
	v_add_f32_e32 v162, v173, v2
	v_add_f32_e32 v163, v174, v2
	v_add_f32_e32 v164, v175, v2
	v_exp_f32_e32 v155, v148
	v_add_f32_e32 v148, v156, v2
	v_exp_f32_e32 v161, v161
	v_exp_f32_e32 v162, v162
	v_exp_f32_e32 v163, v163
	v_exp_f32_e32 v164, v164
	v_add_f32_e32 v144, v144, v2
	v_add_f32_e32 v145, v145, v2
	v_add_f32_e32 v146, v146, v2
	v_add_f32_e32 v147, v147, v2
	v_exp_f32_e32 v156, v148
	v_add_f32_e32 v148, v157, v2
	v_exp_f32_e32 v144, v144
	v_exp_f32_e32 v145, v145
	v_exp_f32_e32 v146, v146
	v_exp_f32_e32 v147, v147
	v_exp_f32_e32 v157, v148
	v_add_f32_e32 v148, v158, v2
	v_add_f32_e32 v2, v159, v2
	v_exp_f32_e32 v158, v148
	v_exp_f32_e32 v159, v2
	v_add_f32_e32 v2, v7, v3
	v_add_f32_e32 v148, v8, v4
	v_add_f32_e32 v149, v9, v5
	v_add_f32_e32 v167, v10, v6
	v_add_f32_e32 v2, v11, v2
	v_add_f32_e32 v148, v12, v148
	v_add_f32_e32 v149, v13, v149
	v_add_f32_e32 v167, v160, v167
	v_add_f32_e32 v2, v161, v2
	v_add_f32_e32 v148, v162, v148
	v_add_f32_e32 v149, v163, v149
	v_add_f32_e32 v167, v164, v167
	v_add_f32_e32 v2, v144, v2
	v_add_f32_e32 v148, v145, v148
	v_add_f32_e32 v149, v146, v149
	v_add_f32_e32 v167, v147, v167
	v_add_f32_e32 v2, v165, v2
	v_add_f32_e32 v148, v166, v148
	v_add_f32_e32 v149, v150, v149
	v_add_f32_e32 v167, v151, v167
	v_add_f32_e32 v2, v152, v2
	v_add_f32_e32 v148, v153, v148
	v_add_f32_e32 v149, v154, v149
	v_add_f32_e32 v167, v155, v167
	v_add_f32_e32 v2, v156, v2
	v_add_f32_e32 v148, v157, v148
	v_add_f32_e32 v149, v158, v149
	v_add_f32_e32 v167, v159, v167
	v_add_f32_e32 v2, v2, v148
	v_add_f32_e32 v148, v149, v167
	v_add_f32_e32 v148, v2, v148
	v_mov_b32_e32 v149, v148
	v_cvt_pk_bf16_f32 v2, v3, v4
	v_cvt_pk_bf16_f32 v3, v5, v6
	v_cvt_pk_bf16_f32 v4, v7, v8
	v_cvt_pk_bf16_f32 v5, v9, v10
	v_cvt_pk_bf16_f32 v6, v11, v12
	v_cvt_pk_bf16_f32 v7, v13, v160
	v_cvt_pk_bf16_f32 v8, v161, v162
	v_cvt_pk_bf16_f32 v9, v163, v164
	v_cvt_pk_bf16_f32 v10, v144, v145
	v_cvt_pk_bf16_f32 v11, v146, v147
	v_cvt_pk_bf16_f32 v12, v165, v166
	v_cvt_pk_bf16_f32 v13, v150, v151
	v_cvt_pk_bf16_f32 v144, v152, v153
	v_cvt_pk_bf16_f32 v145, v154, v155
	v_cvt_pk_bf16_f32 v146, v156, v157
	v_cvt_pk_bf16_f32 v147, v158, v159
	s_nop 1
	v_permlane32_swap_b32_e32 v148, v149
	v_cmp_gt_f32_e32 vcc, 1.0, v223
	s_cbranch_vccz .LBB0_347
	s_and_saveexec_b64 s[6:7], s[4:5]
	ds_write_b32 v215, v223 offset:128
	s_or_b64 exec, exec, s[6:7]
	s_waitcnt lgkmcnt(0)
	ds_read_b128 v[150:153], v216 offset:224
	ds_read_b128 v[154:157], v216 offset:192
	ds_read_b128 v[158:161], v216 offset:160
	ds_read_b128 v[162:165], v216 offset:128
	s_waitcnt lgkmcnt(3)
	v_pk_mul_f32 v[126:127], v[126:127], v[152:153]
	s_waitcnt lgkmcnt(2)
	v_pk_mul_f32 v[122:123], v[122:123], v[156:157]
	s_waitcnt lgkmcnt(1)
	v_pk_mul_f32 v[118:119], v[118:119], v[160:161]
	s_waitcnt lgkmcnt(0)
	v_pk_mul_f32 v[114:115], v[114:115], v[164:165]
	v_pk_mul_f32 v[124:125], v[124:125], v[150:151]
	v_pk_mul_f32 v[120:121], v[120:121], v[154:155]
	v_pk_mul_f32 v[116:117], v[116:117], v[158:159]
	v_pk_mul_f32 v[112:113], v[112:113], v[162:163]
	v_pk_mul_f32 v[78:79], v[78:79], v[152:153]
	v_pk_mul_f32 v[74:75], v[74:75], v[156:157]
	v_pk_mul_f32 v[70:71], v[70:71], v[160:161]
	v_pk_mul_f32 v[66:67], v[66:67], v[164:165]
	v_pk_mul_f32 v[76:77], v[76:77], v[150:151]
	v_pk_mul_f32 v[72:73], v[72:73], v[154:155]
	v_pk_mul_f32 v[68:69], v[68:69], v[158:159]
	v_pk_mul_f32 v[64:65], v[64:65], v[162:163]
	v_pk_mul_f32 v[30:31], v[30:31], v[152:153]
	v_pk_mul_f32 v[26:27], v[26:27], v[156:157]
	v_pk_mul_f32 v[22:23], v[22:23], v[160:161]
	v_pk_mul_f32 v[18:19], v[18:19], v[164:165]
	v_pk_mul_f32 v[28:29], v[28:29], v[150:151]
	v_pk_mul_f32 v[24:25], v[24:25], v[154:155]
	v_pk_mul_f32 v[20:21], v[20:21], v[158:159]
	v_pk_mul_f32 v[16:17], v[16:17], v[162:163]
	v_pk_mul_f32 v[46:47], v[46:47], v[152:153]
	v_pk_mul_f32 v[42:43], v[42:43], v[156:157]
	v_pk_mul_f32 v[38:39], v[38:39], v[160:161]
	v_pk_mul_f32 v[34:35], v[34:35], v[164:165]
	v_pk_mul_f32 v[44:45], v[44:45], v[150:151]
	v_pk_mul_f32 v[40:41], v[40:41], v[154:155]
	v_pk_mul_f32 v[36:37], v[36:37], v[158:159]
	v_pk_mul_f32 v[32:33], v[32:33], v[162:163]
; __device__ __forceinline__ void pv_d0(f32x16* o, int vb, bf16x8 pa0, bf16x8 pa1, bf16x8 pa2, bf16x8 pa3) {
;     ...
;   const s16x4 l0 = tr_read<v_rd_off(0, 0, 0)>(vb), h0 = tr_read<v_rd_off(0, 0, 1)>(vb);
;   const s16x4 l1 = tr_read<v_rd_off(0, 1, 0)>(vb), h1 = tr_read<v_rd_off(0, 1, 1)>(vb);
;   const s16x4 l2 = tr_read<v_rd_off(0, 2, 0)>(vb), h2 = tr_read<v_rd_off(0, 2, 1)>(vb);
;   const s16x4 l3 = tr_read<v_rd_off(0, 3, 0)>(vb), h3 = tr_read<v_rd_off(0, 3, 1)>(vb);
;   const s16x4 l4 = tr_read<v_rd_off(1, 0, 0)>(vb), h4 = tr_read<v_rd_off(1, 0, 1)>(vb);
;   asm volatile("s_waitcnt lgkmcnt(8)" ::: "memory"); SBAR();
;   o[0] = __builtin_amdgcn_mfma_f32_32x32x16_bf16(pa0, PK(l0, h0), o[0], 0, 0, 0);
;   const s16x4 l5 = tr_read<v_rd_off(1, 1, 0)>(vb), h5 = tr_read<v_rd_off(1, 1, 1)>(vb);
;   asm volatile("s_waitcnt lgkmcnt(8)" ::: "memory"); SBAR();
;   o[0] = __builtin_amdgcn_mfma_f32_32x32x16_bf16(pa1, PK(l1, h1), o[0], 0, 0, 0);
;   const s16x4 l6 = tr_read<v_rd_off(1, 2, 0)>(vb), h6 = tr_read<v_rd_off(1, 2, 1)>(vb);
;   asm volatile("s_waitcnt lgkmcnt(8)" ::: "memory"); SBAR();
;   o[0] = __builtin_amdgcn_mfma_f32_32x32x16_bf16(pa2, PK(l2, h2), o[0], 0, 0, 0);
;   const s16x4 l7 = tr_read<v_rd_off(1, 3, 0)>(vb), h7 = tr_read<v_rd_off(1, 3, 1)>(vb);
;   asm volatile("s_waitcnt lgkmcnt(8)" ::: "memory"); SBAR();
;   o[0] = __builtin_amdgcn_mfma_f32_32x32x16_bf16(pa3, PK(l3, h3), o[0], 0, 0, 0);
;   const s16x4 l8 = tr_read<v_rd_off(2, 0, 0)>(vb), h8 = tr_read<v_rd_off(2, 0, 1)>(vb);
;   asm volatile("s_waitcnt lgkmcnt(8)" ::: "memory"); SBAR();
;   o[1] = __builtin_amdgcn_mfma_f32_32x32x16_bf16(pa0, PK(l4, h4), o[1], 0, 0, 0);
;   const s16x4 l9 = tr_read<v_rd_off(2, 1, 0)>(vb), h9 = tr_read<v_rd_off(2, 1, 1)>(vb);
;   asm volatile("s_waitcnt lgkmcnt(8)" ::: "memory"); SBAR();
;   o[1] = __builtin_amdgcn_mfma_f32_32x32x16_bf16(pa1, PK(l5, h5), o[1], 0, 0, 0);
;   const s16x4 l10 = tr_read<v_rd_off(2, 2, 0)>(vb), h10 = tr_read<v_rd_off(2, 2, 1)>(vb);
;   asm volatile("s_waitcnt lgkmcnt(8)" ::: "memory"); SBAR();
;   o[1] = __builtin_amdgcn_mfma_f32_32x32x16_bf16(pa2, PK(l6, h6), o[1], 0, 0, 0);
;   const s16x4 l11 = tr_read<v_rd_off(2, 3, 0)>(vb), h11 = tr_read<v_rd_off(2, 3, 1)>(vb);
;   asm volatile("s_waitcnt lgkmcnt(8)" ::: "memory"); SBAR();
;   o[1] = __builtin_amdgcn_mfma_f32_32x32x16_bf16(pa3, PK(l7, h7), o[1], 0, 0, 0);
.LBB0_347:
.LBB0_349:
	ds_read_b64_tr_b16 v[150:151], v222 offset:0
	ds_read_b64_tr_b16 v[152:153], v222 offset:0x800
	ds_read_b64_tr_b16 v[154:155], v222 offset:0x1000
	ds_read_b64_tr_b16 v[156:157], v222 offset:0x1800
	ds_read_b64_tr_b16 v[158:159], v222 offset:0x2000
	ds_read_b64_tr_b16 v[160:161], v222 offset:0x2800
	ds_read_b64_tr_b16 v[162:163], v222 offset:0x3000
	ds_read_b64_tr_b16 v[164:165], v222 offset:0x3800
	ds_read_b64_tr_b16 v[166:167], v222 offset:0x200
	ds_read_b64_tr_b16 v[168:169], v222 offset:0xa00
	s_waitcnt lgkmcnt(8)
	s_nop 0
	v_mfma_f32_32x32x16_bf16 v[112:127], v[2:5], v[150:153], v[112:127]
	ds_read_b64_tr_b16 v[150:151], v222 offset:0x1200
	ds_read_b64_tr_b16 v[152:153], v222 offset:0x1a00
	s_waitcnt lgkmcnt(8)
	v_mfma_f32_32x32x16_bf16 v[112:127], v[6:9], v[154:157], v[112:127]
	ds_read_b64_tr_b16 v[154:155], v222 offset:0x2200
	ds_read_b64_tr_b16 v[156:157], v222 offset:0x2a00
	s_waitcnt lgkmcnt(8)
	v_mfma_f32_32x32x16_bf16 v[112:127], v[10:13], v[158:161], v[112:127]
	ds_read_b64_tr_b16 v[158:159], v222 offset:0x3200
	ds_read_b64_tr_b16 v[160:161], v222 offset:0x3a00
	s_waitcnt lgkmcnt(8)
	v_mfma_f32_32x32x16_bf16 v[112:127], v[144:147], v[162:165], v[112:127]
	ds_read_b64_tr_b16 v[162:163], v222 offset:0x400
	ds_read_b64_tr_b16 v[164:165], v222 offset:0xc00
	s_waitcnt lgkmcnt(8)
	v_mfma_f32_32x32x16_bf16 v[64:79], v[2:5], v[166:169], v[64:79]
	ds_read_b64_tr_b16 v[166:167], v222 offset:0x1400
	ds_read_b64_tr_b16 v[168:169], v222 offset:0x1c00
	s_waitcnt lgkmcnt(8)
	v_mfma_f32_32x32x16_bf16 v[64:79], v[6:9], v[150:153], v[64:79]
	ds_read_b64_tr_b16 v[150:151], v222 offset:0x2400
	ds_read_b64_tr_b16 v[152:153], v222 offset:0x2c00
	s_waitcnt lgkmcnt(8)
	v_mfma_f32_32x32x16_bf16 v[64:79], v[10:13], v[154:157], v[64:79]
	ds_read_b64_tr_b16 v[154:155], v222 offset:0x3400
	ds_read_b64_tr_b16 v[156:157], v222 offset:0x3c00
	s_waitcnt lgkmcnt(8)
	v_mfma_f32_32x32x16_bf16 v[64:79], v[144:147], v[158:161], v[64:79]
	ds_read_b64_tr_b16 v[158:159], v222 offset:0x600
	ds_read_b64_tr_b16 v[160:161], v222 offset:0xe00
	s_waitcnt lgkmcnt(8)
	v_mfma_f32_32x32x16_bf16 v[16:31], v[2:5], v[162:165], v[16:31]
	ds_read_b64_tr_b16 v[162:163], v222 offset:0x1600
	ds_read_b64_tr_b16 v[164:165], v222 offset:0x1e00
	s_waitcnt lgkmcnt(8)
	v_mfma_f32_32x32x16_bf16 v[16:31], v[6:9], v[166:169], v[16:31]
	ds_read_b64_tr_b16 v[166:167], v222 offset:0x2600
	ds_read_b64_tr_b16 v[168:169], v222 offset:0x2e00
	s_waitcnt lgkmcnt(8)
	v_mfma_f32_32x32x16_bf16 v[16:31], v[10:13], v[150:153], v[16:31]
	ds_read_b64_tr_b16 v[150:151], v222 offset:0x3600
	ds_read_b64_tr_b16 v[152:153], v222 offset:0x3e00
	s_waitcnt lgkmcnt(8)
	v_mfma_f32_32x32x16_bf16 v[16:31], v[144:147], v[154:157], v[16:31]
	s_waitcnt lgkmcnt(6)
	v_mfma_f32_32x32x16_bf16 v[32:47], v[2:5], v[158:161], v[32:47]
	s_waitcnt lgkmcnt(4)
	v_mfma_f32_32x32x16_bf16 v[32:47], v[6:9], v[162:165], v[32:47]
	s_waitcnt lgkmcnt(2)
	v_mfma_f32_32x32x16_bf16 v[32:47], v[10:13], v[166:169], v[32:47]
	s_waitcnt lgkmcnt(0)
	v_mfma_f32_32x32x16_bf16 v[32:47], v[144:147], v[150:153], v[32:47]
